# decode combine task: wait for the split units moved behind the new-key scoring (overlaps the wait)
# speedup vs baseline: 1.1293x; 1.0212x over previous
.LBB0_813:
	s_or_b64 exec, exec, s[0:1]
	s_waitcnt lgkmcnt(0)
	s_barrier
	ds_read_b32 v2, v70
	s_mov_b64 s[0:1], -1
	s_waitcnt lgkmcnt(0)
	s_barrier
	v_readfirstlane_b32 s5, v2
	s_cmp_gt_i32 s5, 63
	s_cbranch_scc1 .LBB0_808
	s_ashr_i32 s0, s5, 31
	s_lshr_b32 s0, s0, 26
	s_add_i32 s4, s5, s0
	s_and_b32 s0, s4, 0xffc0
	s_sub_i32 s9, s5, s0
	s_bfe_i32 s0, s9, 0x80000
	s_bfe_u32 s0, s0, 0x3000c
	s_add_i32 s0, s9, s0
	s_bfe_i32 s0, s0, 0x80000
	s_sext_i32_i16 s10, s0
	v_mov_b32_e32 v44, v0
	s_ashr_i32 s8, s10, 3
	s_nop 0
	v_readfirstlane_b32 s29, v44
	v_cmp_gt_i32_e32 vcc, 64, v44
	s_and_saveexec_b64 s[0:1], vcc
	s_cbranch_execz .LBB0_824
	s_ashr_i32 s4, s4, 6
	s_lshl_b32 s4, s4, 9
	s_ashr_i32 s5, s4, 31
	s_lshl_b64 s[4:5], s[4:5], 2
	s_add_u32 s6, s93, s4
	v_readlane_b32 s4, v255, 1
	s_addc_u32 s7, s4, s5
	s_lshl_b32 s4, s8, 6
	s_ashr_i32 s5, s4, 31
	s_lshl_b64 s[4:5], s[4:5], 2
	s_add_u32 s4, s6, s4
	s_addc_u32 s5, s7, s5
	s_mov_b32 s11, 0x400001
	s_mov_b64 s[100:101], s[4:5]
	s_branch .LBB0_824
.LBB0_824:
	s_or_b64 exec, exec, s[0:1]
	s_lshr_b32 s21, s10, 3
	s_lshl_b32 s0, s21, 3
	s_lshl_b32 s6, s8, 3
	s_sub_i32 s20, s9, s0
	v_and_b32_e32 v4, 7, v44
	s_add_i32 s0, s6, 0x2000
	s_sext_i32_i8 s42, s20
	v_or_b32_e32 v2, s0, v4
	v_readlane_b32 s0, v254, 57
	v_and_b32_e32 v5, 8, v44
	v_readlane_b32 s1, v254, 58
	v_add_u32_e32 v10, s42, v5
	v_lshlrev_b32_e32 v12, 6, v10
	v_mov_b64_e32 v[6:7], s[0:1]
	v_mad_u64_u32 v[6:7], s[0:1], v2, s35, v[6:7]
	v_ashrrev_i32_e32 v13, 31, v12
	v_lshl_add_u64 v[6:7], v[12:13], 1, v[6:7]
	v_add_co_u32_e32 v8, vcc, s36, v6
	s_nop 1
	v_addc_co_u32_e32 v9, vcc, 0, v7, vcc
	v_lshl_add_u64 v[6:7], v[6:7], 0, s[2:3]
	global_load_dwordx4 v[16:19], v[8:9], off
	global_load_dwordx4 v[20:23], v[6:7], off offset:16
	global_load_dwordx4 v[24:27], v[6:7], off offset:32
	global_load_dwordx4 v[28:31], v[6:7], off offset:48
	global_load_dwordx4 v[32:35], v[6:7], off offset:64
	global_load_dwordx4 v[54:57], v[6:7], off offset:80
	global_load_dwordx4 v[88:91], v[6:7], off offset:96
	global_load_dwordx4 v[92:95], v[6:7], off offset:112
	s_ashr_i32 s7, s6, 31
	s_ashr_i32 s28, s29, 6
	v_and_b32_e32 v46, 15, v44
	s_lshl_b64 s[0:1], s[6:7], 12
	s_add_i32 s4, s6, s42
	v_lshl_or_b32 v8, s4, 4, v46
	s_add_u32 s4, s22, s0
	s_addc_u32 s5, s23, s1
	v_lshlrev_b64 v[12:13], 2, v[12:13]
	v_lshl_add_u64 v[148:149], s[4:5], 0, v[12:13]
	global_load_dwordx4 v[96:99], v[148:149], off offset:16
	global_load_dwordx4 v[100:103], v[148:149], off
	global_load_dwordx4 v[104:107], v[148:149], off offset:48
	global_load_dwordx4 v[108:111], v[148:149], off offset:32
	global_load_dwordx4 v[112:115], v[148:149], off offset:112
	global_load_dwordx4 v[116:119], v[148:149], off offset:96
	global_load_dwordx4 v[120:123], v[148:149], off offset:80
	global_load_dwordx4 v[124:127], v[148:149], off offset:64
	global_load_dwordx4 v[128:131], v[148:149], off offset:144
	global_load_dwordx4 v[132:135], v[148:149], off offset:128
	global_load_dwordx4 v[136:139], v[148:149], off offset:176
	global_load_dwordx4 v[140:143], v[148:149], off offset:160
	v_ashrrev_i32_e32 v9, 31, v8
	v_readlane_b32 s4, v254, 4
	v_lshlrev_b64 v[6:7], 6, v[8:9]
	v_readlane_b32 s5, v254, 5
	v_bfe_u32 v74, v44, 4, 2
	s_waitcnt vmcnt(18)
	v_and_b32_e32 v41, 0xffff0000, v20
	v_and_b32_e32 v42, 0xffff0000, v21
	v_and_b32_e32 v43, 0xffff0000, v22
	v_and_b32_e32 v51, 0xffff0000, v23
	v_lshlrev_b32_e32 v14, 16, v16
	v_and_b32_e32 v37, 0xffff0000, v16
	v_lshlrev_b32_e32 v15, 16, v17
	v_and_b32_e32 v38, 0xffff0000, v17
	v_lshlrev_b32_e32 v16, 16, v18
	v_and_b32_e32 v39, 0xffff0000, v18
	v_lshlrev_b32_e32 v17, 16, v19
	v_and_b32_e32 v40, 0xffff0000, v19
	v_lshlrev_b32_e32 v18, 16, v20
	v_lshlrev_b32_e32 v19, 16, v21
	v_lshlrev_b32_e32 v20, 16, v22
	v_lshlrev_b32_e32 v21, 16, v23
	s_waitcnt vmcnt(17)
	v_lshlrev_b32_e32 v22, 16, v24
	v_and_b32_e32 v52, 0xffff0000, v24
	v_lshlrev_b32_e32 v23, 16, v25
	v_and_b32_e32 v59, 0xffff0000, v25
	v_lshlrev_b32_e32 v24, 16, v26
	v_and_b32_e32 v60, 0xffff0000, v26
	v_lshlrev_b32_e32 v25, 16, v27
	v_and_b32_e32 v65, 0xffff0000, v27
	s_waitcnt vmcnt(16)
	v_lshlrev_b32_e32 v26, 16, v28
	v_and_b32_e32 v66, 0xffff0000, v28
	v_lshlrev_b32_e32 v27, 16, v29
	v_and_b32_e32 v67, 0xffff0000, v29
	v_lshlrev_b32_e32 v28, 16, v30
	v_and_b32_e32 v69, 0xffff0000, v30
	v_lshlrev_b32_e32 v29, 16, v31
	v_and_b32_e32 v75, 0xffff0000, v31
	s_waitcnt vmcnt(15)
	v_lshlrev_b32_e32 v30, 16, v32
	v_and_b32_e32 v76, 0xffff0000, v32
	v_lshlrev_b32_e32 v31, 16, v33
	v_and_b32_e32 v77, 0xffff0000, v33
	v_lshlrev_b32_e32 v32, 16, v34
	v_and_b32_e32 v78, 0xffff0000, v34
	v_lshlrev_b32_e32 v33, 16, v35
	v_and_b32_e32 v79, 0xffff0000, v35
	s_waitcnt vmcnt(14)
	v_lshlrev_b32_e32 v34, 16, v54
	v_and_b32_e32 v80, 0xffff0000, v54
	v_lshlrev_b32_e32 v35, 16, v55
	v_and_b32_e32 v81, 0xffff0000, v55
	v_lshlrev_b32_e32 v36, 16, v56
	v_and_b32_e32 v82, 0xffff0000, v56
	s_waitcnt vmcnt(13)
	v_lshlrev_b32_e32 v53, 16, v90
	v_and_b32_e32 v61, 0xffff0000, v90
	v_lshlrev_b32_e32 v54, 16, v91
	v_and_b32_e32 v62, 0xffff0000, v91
	s_waitcnt vmcnt(12)
	v_lshlrev_b32_e32 v55, 16, v92
	v_and_b32_e32 v63, 0xffff0000, v92
	v_lshlrev_b32_e32 v56, 16, v93
	v_and_b32_e32 v64, 0xffff0000, v93
	global_load_dwordx4 v[90:93], v[148:149], off offset:208
	global_load_dwordx4 v[144:147], v[148:149], off offset:192
	s_waitcnt vmcnt(12)
	v_mul_f32_e32 v5, v101, v37
	v_mul_f32_e32 v11, v103, v38
	v_mul_f32_e32 v45, v97, v39
	v_lshlrev_b32_e32 v83, 16, v57
	v_and_b32_e32 v86, 0xffff0000, v57
	v_lshlrev_b32_e32 v49, 16, v94
	v_and_b32_e32 v57, 0xffff0000, v94
	v_lshlrev_b32_e32 v50, 16, v95
	v_and_b32_e32 v58, 0xffff0000, v95
	v_fmac_f32_e32 v5, v100, v14
	v_fmac_f32_e32 v11, v102, v15
	v_fmac_f32_e32 v45, v96, v16
	global_load_dwordx4 v[94:97], v[148:149], off offset:240
	global_load_dwordx4 v[100:103], v[148:149], off offset:224
	v_mul_f32_e32 v47, v99, v40
	v_add_f32_e32 v11, v5, v11
	v_fmac_f32_e32 v47, v98, v17
	v_add_f32_e32 v11, 0, v11
	v_add_f32_e32 v45, v45, v47
	v_lshl_add_u32 v98, v4, 4, v10
	v_add_f32_e32 v11, v11, v45
	s_waitcnt vmcnt(12)
	v_mul_f32_e32 v45, v109, v41
	v_mul_f32_e32 v47, v111, v42
	v_ashrrev_i32_e32 v99, 31, v98
	v_fmac_f32_e32 v45, v108, v18
	v_fmac_f32_e32 v47, v110, v19
	v_lshl_add_u64 v[98:99], v[98:99], 2, s[48:49]
	v_add_f32_e32 v45, v45, v47
	global_load_dword v47, v[98:99], off
	v_add_f32_e32 v11, v11, v45
	v_mul_f32_e32 v45, v105, v43
	v_mul_f32_e32 v48, v107, v51
	v_fmac_f32_e32 v45, v104, v20
	v_fmac_f32_e32 v48, v106, v21
	v_add_f32_e32 v45, v45, v48
	v_add_f32_e32 v11, v11, v45
	s_waitcnt vmcnt(9)
	v_mul_f32_e32 v45, v125, v52
	v_mul_f32_e32 v48, v127, v59
	v_fmac_f32_e32 v45, v124, v22
	v_fmac_f32_e32 v48, v126, v23
	v_add_f32_e32 v45, v45, v48
	v_add_f32_e32 v11, v11, v45
	v_mul_f32_e32 v45, v121, v60
	v_mul_f32_e32 v48, v123, v65
	v_fmac_f32_e32 v45, v120, v24
	v_fmac_f32_e32 v48, v122, v25
	v_add_f32_e32 v45, v45, v48
	v_add_f32_e32 v11, v11, v45
	v_mul_f32_e32 v45, v117, v66
	v_mul_f32_e32 v48, v119, v67
	v_fmac_f32_e32 v45, v116, v26
	v_fmac_f32_e32 v48, v118, v27
	v_add_f32_e32 v45, v45, v48
	v_add_f32_e32 v11, v11, v45
	v_mul_f32_e32 v45, v113, v69
	v_mul_f32_e32 v48, v115, v75
	v_fmac_f32_e32 v45, v112, v28
	v_fmac_f32_e32 v48, v114, v29
	v_add_f32_e32 v45, v45, v48
	v_add_f32_e32 v11, v11, v45
	s_waitcnt vmcnt(7)
	v_mul_f32_e32 v45, v133, v76
	v_mul_f32_e32 v48, v135, v77
	v_fmac_f32_e32 v45, v132, v30
	v_fmac_f32_e32 v48, v134, v31
	v_add_f32_e32 v45, v45, v48
	v_add_f32_e32 v11, v11, v45
	v_mul_f32_e32 v45, v129, v78
	v_mul_f32_e32 v48, v131, v79
	v_fmac_f32_e32 v45, v128, v32
	v_fmac_f32_e32 v48, v130, v33
	v_add_f32_e32 v45, v45, v48
	v_add_f32_e32 v11, v11, v45
	s_waitcnt vmcnt(5)
	v_mul_f32_e32 v45, v141, v80
	v_mul_f32_e32 v48, v143, v81
	v_fmac_f32_e32 v45, v140, v34
	v_fmac_f32_e32 v48, v142, v35
	v_add_f32_e32 v45, v45, v48
	v_add_f32_e32 v11, v11, v45
	v_mul_f32_e32 v45, v137, v82
	v_mul_f32_e32 v48, v139, v86
	v_fmac_f32_e32 v45, v136, v36
	v_fmac_f32_e32 v48, v138, v83
	v_lshlrev_b32_e32 v84, 16, v88
	v_and_b32_e32 v87, 0xffff0000, v88
	v_and_b32_e32 v88, 0xffff0000, v89
	v_add_f32_e32 v45, v45, v48
	v_lshlrev_b32_e32 v85, 16, v89
	v_add_f32_e32 v11, v11, v45
	s_waitcnt vmcnt(3)
	v_mul_f32_e32 v45, v145, v87
	v_mul_f32_e32 v48, v147, v88
	v_fmac_f32_e32 v45, v144, v84
	v_fmac_f32_e32 v48, v146, v85
	v_add_f32_e32 v45, v45, v48
	v_add_f32_e32 v11, v11, v45
	v_mul_f32_e32 v45, v91, v61
	v_mul_f32_e32 v48, v93, v62
	v_fmac_f32_e32 v45, v90, v53
	v_fmac_f32_e32 v48, v92, v54
	v_add_f32_e32 v45, v45, v48
	v_add_f32_e32 v11, v11, v45
	s_waitcnt vmcnt(1)
	v_mul_f32_e32 v45, v101, v63
	v_mul_f32_e32 v48, v103, v64
	v_fmac_f32_e32 v45, v100, v55
	v_fmac_f32_e32 v48, v102, v56
	v_add_f32_e32 v45, v45, v48
	v_add_f32_e32 v11, v11, v45
	v_mul_f32_e32 v45, v95, v57
	v_mul_f32_e32 v48, v97, v58
	v_fmac_f32_e32 v45, v94, v49
	v_fmac_f32_e32 v48, v96, v50
	v_add_f32_e32 v45, v45, v48
	v_add_f32_e32 v45, v11, v45
	v_lshl_add_u64 v[6:7], s[4:5], 0, v[6:7]
	v_mov_b32_e32 v5, 0
	s_waitcnt vmcnt(0)
	v_fmac_f32_e32 v45, 0x3fb8aa3b, v47
	s_or_b32 s4, s6, 1
	s_ashr_i32 s5, s4, 31
	s_lshl_b64 s[4:5], s[4:5], 12
	s_add_u32 s8, s22, s4
	s_addc_u32 s9, s23, s5
	v_lshl_add_u64 v[150:151], s[8:9], 0, v[12:13]
	global_load_dwordx4 v[90:93], v[150:151], off
	global_load_dwordx4 v[94:97], v[150:151], off offset:16
	global_load_dwordx4 v[98:101], v[150:151], off offset:32
	global_load_dwordx4 v[102:105], v[150:151], off offset:48
	global_load_dwordx4 v[106:109], v[150:151], off offset:64
	global_load_dwordx4 v[110:113], v[150:151], off offset:80
	global_load_dwordx4 v[114:117], v[150:151], off offset:96
	global_load_dwordx4 v[118:121], v[150:151], off offset:112
	global_load_dwordx4 v[122:125], v[150:151], off offset:128
	global_load_dwordx4 v[126:129], v[150:151], off offset:144
	global_load_dwordx4 v[130:133], v[150:151], off offset:160
	global_load_dwordx4 v[134:137], v[150:151], off offset:176
	global_load_dwordx4 v[138:141], v[150:151], off offset:208
	global_load_dwordx4 v[142:145], v[150:151], off offset:192
	v_max_i32_e32 v47, 1, v4
	v_mov_b32_e32 v147, v3
	v_ashrrev_i32_e32 v11, 31, v10
	v_lshlrev_b32_e32 v146, 4, v47
	v_lshl_add_u64 v[146:147], v[10:11], 0, v[146:147]
	v_lshl_add_u64 v[146:147], v[146:147], 2, s[48:49]
	global_load_dword v47, v[146:147], off offset:-64
	s_nop 0
	global_load_dwordx4 v[146:149], v[150:151], off offset:240
	s_nop 0
	global_load_dwordx4 v[150:153], v[150:151], off offset:224
	v_cmp_ne_u32_e32 vcc, 0, v4
	s_waitcnt vmcnt(16)
	v_mul_f32_e32 v48, v91, v37
	v_mul_f32_e32 v68, v93, v38
	s_waitcnt vmcnt(15)
	v_mul_f32_e32 v89, v95, v39
	v_mul_f32_e32 v91, v97, v40
	v_fmac_f32_e32 v48, v90, v14
	v_fmac_f32_e32 v68, v92, v15
	s_waitcnt vmcnt(14)
	v_mul_f32_e32 v93, v99, v41
	v_mul_f32_e32 v95, v101, v42
	v_fmac_f32_e32 v89, v94, v16
	v_fmac_f32_e32 v91, v96, v17
	v_add_f32_e32 v48, v48, v68
	s_waitcnt vmcnt(13)
	v_mul_f32_e32 v97, v103, v43
	v_mul_f32_e32 v99, v105, v51
	v_fmac_f32_e32 v93, v98, v18
	v_fmac_f32_e32 v95, v100, v19
	v_add_f32_e32 v68, v89, v91
	v_add_f32_e32 v48, 0, v48
	s_waitcnt vmcnt(12)
	v_mul_f32_e32 v101, v107, v52
	v_mul_f32_e32 v103, v109, v59
	v_fmac_f32_e32 v97, v102, v20
	v_fmac_f32_e32 v99, v104, v21
	v_add_f32_e32 v89, v93, v95
	v_add_f32_e32 v48, v48, v68
	s_waitcnt vmcnt(11)
	v_mul_f32_e32 v105, v111, v60
	v_mul_f32_e32 v107, v113, v65
	v_fmac_f32_e32 v101, v106, v22
	v_fmac_f32_e32 v103, v108, v23
	v_add_f32_e32 v90, v97, v99
	v_add_f32_e32 v48, v48, v89
	s_waitcnt vmcnt(10)
	v_mul_f32_e32 v109, v115, v66
	v_mul_f32_e32 v111, v117, v67
	v_fmac_f32_e32 v105, v110, v24
	v_fmac_f32_e32 v107, v112, v25
	v_add_f32_e32 v91, v101, v103
	v_add_f32_e32 v48, v48, v90
	s_waitcnt vmcnt(9)
	v_mul_f32_e32 v113, v119, v69
	v_mul_f32_e32 v115, v121, v75
	v_fmac_f32_e32 v109, v114, v26
	v_fmac_f32_e32 v111, v116, v27
	v_add_f32_e32 v92, v105, v107
	v_add_f32_e32 v48, v48, v91
	s_waitcnt vmcnt(8)
	v_mul_f32_e32 v117, v123, v76
	v_mul_f32_e32 v119, v125, v77
	v_fmac_f32_e32 v113, v118, v28
	v_fmac_f32_e32 v115, v120, v29
	v_add_f32_e32 v93, v109, v111
	v_add_f32_e32 v48, v48, v92
	s_waitcnt vmcnt(7)
	v_mul_f32_e32 v121, v127, v78
	v_mul_f32_e32 v123, v129, v79
	v_fmac_f32_e32 v117, v122, v30
	v_fmac_f32_e32 v119, v124, v31
	v_add_f32_e32 v94, v113, v115
	v_add_f32_e32 v48, v48, v93
	s_waitcnt vmcnt(6)
	v_mul_f32_e32 v125, v131, v80
	v_mul_f32_e32 v127, v133, v81
	v_fmac_f32_e32 v121, v126, v32
	v_fmac_f32_e32 v123, v128, v33
	v_add_f32_e32 v95, v117, v119
	v_add_f32_e32 v48, v48, v94
	s_waitcnt vmcnt(5)
	v_mul_f32_e32 v129, v135, v82
	v_mul_f32_e32 v131, v137, v86
	v_fmac_f32_e32 v125, v130, v34
	v_fmac_f32_e32 v127, v132, v35
	v_add_f32_e32 v96, v121, v123
	v_add_f32_e32 v48, v48, v95
	v_fmac_f32_e32 v129, v134, v36
	v_fmac_f32_e32 v131, v136, v83
	v_add_f32_e32 v97, v125, v127
	v_add_f32_e32 v48, v48, v96
	s_waitcnt vmcnt(3)
	v_mul_f32_e32 v68, v143, v87
	v_mul_f32_e32 v89, v145, v88
	v_add_f32_e32 v98, v129, v131
	v_add_f32_e32 v48, v48, v97
	v_fmac_f32_e32 v68, v142, v84
	v_fmac_f32_e32 v89, v144, v85
	v_add_f32_e32 v48, v48, v98
	v_add_f32_e32 v68, v68, v89
	v_add_f32_e32 v48, v48, v68
	v_mul_f32_e32 v68, v139, v61
	v_mul_f32_e32 v89, v141, v62
	v_fmac_f32_e32 v68, v138, v53
	v_fmac_f32_e32 v89, v140, v54
	v_add_f32_e32 v68, v68, v89
	v_add_f32_e32 v48, v48, v68
	s_waitcnt vmcnt(0)
	v_mul_f32_e32 v68, v151, v63
	v_mul_f32_e32 v89, v153, v64
	v_fmac_f32_e32 v68, v150, v55
	v_fmac_f32_e32 v89, v152, v56
	v_add_f32_e32 v68, v68, v89
	v_add_f32_e32 v48, v48, v68
	v_mul_f32_e32 v68, v147, v57
	v_mul_f32_e32 v89, v149, v58
	v_fmac_f32_e32 v68, v146, v49
	v_fmac_f32_e32 v89, v148, v50
	v_add_f32_e32 v68, v68, v89
	v_add_f32_e32 v48, v48, v68
	v_fmac_f32_e32 v48, 0x3fb8aa3b, v47
	v_cndmask_b32_e32 v47, v73, v48, vcc
	s_or_b32 s8, s6, 2
	s_ashr_i32 s9, s8, 31
	s_lshl_b64 s[8:9], s[8:9], 12
	s_add_u32 s10, s22, s8
	s_addc_u32 s11, s23, s9
	v_lshl_add_u64 v[150:151], s[10:11], 0, v[12:13]
	global_load_dwordx4 v[90:93], v[150:151], off
	global_load_dwordx4 v[94:97], v[150:151], off offset:16
	global_load_dwordx4 v[98:101], v[150:151], off offset:32
	global_load_dwordx4 v[102:105], v[150:151], off offset:48
	global_load_dwordx4 v[106:109], v[150:151], off offset:64
	global_load_dwordx4 v[110:113], v[150:151], off offset:80
	global_load_dwordx4 v[114:117], v[150:151], off offset:96
	global_load_dwordx4 v[118:121], v[150:151], off offset:112
	global_load_dwordx4 v[122:125], v[150:151], off offset:128
	global_load_dwordx4 v[126:129], v[150:151], off offset:144
	global_load_dwordx4 v[130:133], v[150:151], off offset:160
	global_load_dwordx4 v[134:137], v[150:151], off offset:176
	global_load_dwordx4 v[138:141], v[150:151], off offset:192
	global_load_dwordx4 v[142:145], v[150:151], off offset:208
	v_max_i32_e32 v48, 2, v4
	v_mov_b32_e32 v147, v3
	v_lshlrev_b32_e32 v146, 4, v48
	v_lshl_add_u64 v[146:147], v[10:11], 0, v[146:147]
	v_lshl_add_u64 v[146:147], v[146:147], 2, s[48:49]
	global_load_dword v48, v[146:147], off offset:-128
	s_nop 0
	global_load_dwordx4 v[146:149], v[150:151], off offset:240
	s_nop 0
	global_load_dwordx4 v[150:153], v[150:151], off offset:224
	v_cmp_lt_u32_e32 vcc, 1, v4
	s_waitcnt vmcnt(16)
	v_mul_f32_e32 v68, v91, v37
	v_mul_f32_e32 v89, v93, v38
	s_waitcnt vmcnt(15)
	v_mul_f32_e32 v91, v95, v39
	v_mul_f32_e32 v93, v97, v40
	v_fmac_f32_e32 v68, v90, v14
	v_fmac_f32_e32 v89, v92, v15
	s_waitcnt vmcnt(14)
	v_mul_f32_e32 v95, v99, v41
	v_mul_f32_e32 v97, v101, v42
	v_fmac_f32_e32 v91, v94, v16
	v_fmac_f32_e32 v93, v96, v17
	v_add_f32_e32 v68, v68, v89
	s_waitcnt vmcnt(13)
	v_mul_f32_e32 v99, v103, v43
	v_mul_f32_e32 v101, v105, v51
	v_fmac_f32_e32 v95, v98, v18
	v_fmac_f32_e32 v97, v100, v19
	v_add_f32_e32 v89, v91, v93
	v_add_f32_e32 v68, 0, v68
	s_waitcnt vmcnt(12)
	v_mul_f32_e32 v103, v107, v52
	v_mul_f32_e32 v105, v109, v59
	v_fmac_f32_e32 v99, v102, v20
	v_fmac_f32_e32 v101, v104, v21
	v_add_f32_e32 v90, v95, v97
	v_add_f32_e32 v68, v68, v89
	s_waitcnt vmcnt(11)
	v_mul_f32_e32 v107, v111, v60
	v_mul_f32_e32 v109, v113, v65
	v_fmac_f32_e32 v103, v106, v22
	v_fmac_f32_e32 v105, v108, v23
	v_add_f32_e32 v91, v99, v101
	v_add_f32_e32 v68, v68, v90
	s_waitcnt vmcnt(10)
	v_mul_f32_e32 v111, v115, v66
	v_mul_f32_e32 v113, v117, v67
	v_fmac_f32_e32 v107, v110, v24
	v_fmac_f32_e32 v109, v112, v25
	v_add_f32_e32 v92, v103, v105
	v_add_f32_e32 v68, v68, v91
	s_waitcnt vmcnt(9)
	v_mul_f32_e32 v115, v119, v69
	v_mul_f32_e32 v117, v121, v75
	v_fmac_f32_e32 v111, v114, v26
	v_fmac_f32_e32 v113, v116, v27
	v_add_f32_e32 v93, v107, v109
	v_add_f32_e32 v68, v68, v92
	s_waitcnt vmcnt(8)
	v_mul_f32_e32 v119, v123, v76
	v_mul_f32_e32 v121, v125, v77
	v_fmac_f32_e32 v115, v118, v28
	v_fmac_f32_e32 v117, v120, v29
	v_add_f32_e32 v94, v111, v113
	v_add_f32_e32 v68, v68, v93
	s_waitcnt vmcnt(7)
	v_mul_f32_e32 v123, v127, v78
	v_mul_f32_e32 v125, v129, v79
	v_fmac_f32_e32 v119, v122, v30
	v_fmac_f32_e32 v121, v124, v31
	v_add_f32_e32 v95, v115, v117
	v_add_f32_e32 v68, v68, v94
	s_waitcnt vmcnt(6)
	v_mul_f32_e32 v127, v131, v80
	v_mul_f32_e32 v129, v133, v81
	v_fmac_f32_e32 v123, v126, v32
	v_fmac_f32_e32 v125, v128, v33
	v_add_f32_e32 v96, v119, v121
	v_add_f32_e32 v68, v68, v95
	s_waitcnt vmcnt(5)
	v_mul_f32_e32 v131, v135, v82
	v_mul_f32_e32 v133, v137, v86
	v_fmac_f32_e32 v127, v130, v34
	v_fmac_f32_e32 v129, v132, v35
	v_add_f32_e32 v97, v123, v125
	v_add_f32_e32 v68, v68, v96
	s_waitcnt vmcnt(4)
	v_mul_f32_e32 v135, v139, v87
	v_fmac_f32_e32 v131, v134, v36
	v_fmac_f32_e32 v133, v136, v83
	v_add_f32_e32 v98, v127, v129
	v_add_f32_e32 v68, v68, v97
	v_mul_f32_e32 v89, v141, v88
	v_add_f32_e32 v99, v131, v133
	v_add_f32_e32 v68, v68, v98
	v_fmac_f32_e32 v135, v138, v84
	v_fmac_f32_e32 v89, v140, v85
	v_add_f32_e32 v68, v68, v99
	v_add_f32_e32 v89, v135, v89
	v_add_f32_e32 v68, v68, v89
	s_waitcnt vmcnt(3)
	v_mul_f32_e32 v89, v143, v61
	v_mul_f32_e32 v90, v145, v62
	v_fmac_f32_e32 v89, v142, v53
	v_fmac_f32_e32 v90, v144, v54
	v_add_f32_e32 v89, v89, v90
	v_add_f32_e32 v68, v68, v89
	s_waitcnt vmcnt(0)
	v_mul_f32_e32 v89, v151, v63
	v_mul_f32_e32 v90, v153, v64
	v_fmac_f32_e32 v89, v150, v55
	v_fmac_f32_e32 v90, v152, v56
	v_add_f32_e32 v89, v89, v90
	v_add_f32_e32 v68, v68, v89
	v_mul_f32_e32 v89, v147, v57
	v_mul_f32_e32 v90, v149, v58
	v_fmac_f32_e32 v89, v146, v49
	v_fmac_f32_e32 v90, v148, v50
	v_add_f32_e32 v89, v89, v90
	v_add_f32_e32 v68, v68, v89
	v_fmac_f32_e32 v68, 0x3fb8aa3b, v48
	v_cndmask_b32_e32 v48, v73, v68, vcc
	s_or_b32 s10, s6, 3
	s_ashr_i32 s11, s10, 31
	s_lshl_b64 s[10:11], s[10:11], 12
	s_add_u32 s14, s22, s10
	s_addc_u32 s15, s23, s11
	v_lshl_add_u64 v[150:151], s[14:15], 0, v[12:13]
	global_load_dwordx4 v[90:93], v[150:151], off
	global_load_dwordx4 v[94:97], v[150:151], off offset:16
	global_load_dwordx4 v[98:101], v[150:151], off offset:32
	global_load_dwordx4 v[102:105], v[150:151], off offset:48
	global_load_dwordx4 v[106:109], v[150:151], off offset:64
	global_load_dwordx4 v[110:113], v[150:151], off offset:80
	global_load_dwordx4 v[114:117], v[150:151], off offset:96
	global_load_dwordx4 v[118:121], v[150:151], off offset:112
	global_load_dwordx4 v[122:125], v[150:151], off offset:128
	global_load_dwordx4 v[126:129], v[150:151], off offset:144
	global_load_dwordx4 v[130:133], v[150:151], off offset:160
	global_load_dwordx4 v[134:137], v[150:151], off offset:176
	global_load_dwordx4 v[138:141], v[150:151], off offset:192
	global_load_dwordx4 v[142:145], v[150:151], off offset:208
	v_max_i32_e32 v68, 3, v4
	v_mov_b32_e32 v147, v3
	v_lshlrev_b32_e32 v146, 4, v68
	v_lshl_add_u64 v[146:147], v[10:11], 0, v[146:147]
	v_lshl_add_u64 v[146:147], v[146:147], 2, s[48:49]
	global_load_dword v68, v[146:147], off offset:-192
	s_nop 0
	global_load_dwordx4 v[146:149], v[150:151], off offset:240
	s_nop 0
	global_load_dwordx4 v[150:153], v[150:151], off offset:224
	v_cmp_lt_u32_e32 vcc, 2, v4
	s_waitcnt vmcnt(16)
	v_mul_f32_e32 v89, v91, v37
	v_mul_f32_e32 v91, v93, v38
	s_waitcnt vmcnt(15)
	v_mul_f32_e32 v93, v95, v39
	v_mul_f32_e32 v95, v97, v40
	v_fmac_f32_e32 v89, v90, v14
	v_fmac_f32_e32 v91, v92, v15
	s_waitcnt vmcnt(14)
	v_mul_f32_e32 v97, v99, v41
	v_mul_f32_e32 v99, v101, v42
	v_fmac_f32_e32 v93, v94, v16
	v_fmac_f32_e32 v95, v96, v17
	v_add_f32_e32 v89, v89, v91
	s_waitcnt vmcnt(13)
	v_mul_f32_e32 v101, v103, v43
	v_mul_f32_e32 v103, v105, v51
	v_fmac_f32_e32 v97, v98, v18
	v_fmac_f32_e32 v99, v100, v19
	v_add_f32_e32 v90, v93, v95
	v_add_f32_e32 v89, 0, v89
	s_waitcnt vmcnt(12)
	v_mul_f32_e32 v105, v107, v52
	v_mul_f32_e32 v107, v109, v59
	v_fmac_f32_e32 v101, v102, v20
	v_fmac_f32_e32 v103, v104, v21
	v_add_f32_e32 v91, v97, v99
	v_add_f32_e32 v89, v89, v90
	s_waitcnt vmcnt(11)
	v_mul_f32_e32 v109, v111, v60
	v_mul_f32_e32 v111, v113, v65
	v_fmac_f32_e32 v105, v106, v22
	v_fmac_f32_e32 v107, v108, v23
	v_add_f32_e32 v92, v101, v103
	v_add_f32_e32 v89, v89, v91
	s_waitcnt vmcnt(10)
	v_mul_f32_e32 v113, v115, v66
	v_mul_f32_e32 v115, v117, v67
	v_fmac_f32_e32 v109, v110, v24
	v_fmac_f32_e32 v111, v112, v25
	v_add_f32_e32 v93, v105, v107
	v_add_f32_e32 v89, v89, v92
	s_waitcnt vmcnt(9)
	v_mul_f32_e32 v117, v119, v69
	v_mul_f32_e32 v119, v121, v75
	v_fmac_f32_e32 v113, v114, v26
	v_fmac_f32_e32 v115, v116, v27
	v_add_f32_e32 v94, v109, v111
	v_add_f32_e32 v89, v89, v93
	s_waitcnt vmcnt(8)
	v_mul_f32_e32 v121, v123, v76
	v_mul_f32_e32 v123, v125, v77
	v_fmac_f32_e32 v117, v118, v28
	v_fmac_f32_e32 v119, v120, v29
	v_add_f32_e32 v95, v113, v115
	v_add_f32_e32 v89, v89, v94
	s_waitcnt vmcnt(7)
	v_mul_f32_e32 v125, v127, v78
	v_mul_f32_e32 v127, v129, v79
	v_fmac_f32_e32 v121, v122, v30
	v_fmac_f32_e32 v123, v124, v31
	v_add_f32_e32 v96, v117, v119
	v_add_f32_e32 v89, v89, v95
	s_waitcnt vmcnt(6)
	v_mul_f32_e32 v129, v131, v80
	v_mul_f32_e32 v131, v133, v81
	v_fmac_f32_e32 v125, v126, v32
	v_fmac_f32_e32 v127, v128, v33
	v_add_f32_e32 v97, v121, v123
	v_add_f32_e32 v89, v89, v96
	s_waitcnt vmcnt(5)
	v_mul_f32_e32 v133, v135, v82
	v_mul_f32_e32 v135, v137, v86
	v_fmac_f32_e32 v129, v130, v34
	v_fmac_f32_e32 v131, v132, v35
	v_add_f32_e32 v98, v125, v127
	v_add_f32_e32 v89, v89, v97
	s_waitcnt vmcnt(4)
	v_mul_f32_e32 v137, v139, v87
	v_fmac_f32_e32 v133, v134, v36
	v_fmac_f32_e32 v135, v136, v83
	v_add_f32_e32 v99, v129, v131
	v_add_f32_e32 v89, v89, v98
	v_mul_f32_e32 v90, v141, v88
	v_add_f32_e32 v100, v133, v135
	v_add_f32_e32 v89, v89, v99
	v_fmac_f32_e32 v137, v138, v84
	v_fmac_f32_e32 v90, v140, v85
	v_add_f32_e32 v89, v89, v100
	v_add_f32_e32 v90, v137, v90
	v_add_f32_e32 v89, v89, v90
	s_waitcnt vmcnt(3)
	v_mul_f32_e32 v90, v143, v61
	v_mul_f32_e32 v91, v145, v62
	v_fmac_f32_e32 v90, v142, v53
	v_fmac_f32_e32 v91, v144, v54
	v_add_f32_e32 v90, v90, v91
	v_add_f32_e32 v89, v89, v90
	s_waitcnt vmcnt(0)
	v_mul_f32_e32 v90, v151, v63
	v_mul_f32_e32 v91, v153, v64
	v_fmac_f32_e32 v90, v150, v55
	v_fmac_f32_e32 v91, v152, v56
	v_add_f32_e32 v90, v90, v91
	v_add_f32_e32 v89, v89, v90
	v_mul_f32_e32 v90, v147, v57
	v_mul_f32_e32 v91, v149, v58
	v_fmac_f32_e32 v90, v146, v49
	v_fmac_f32_e32 v91, v148, v50
	v_add_f32_e32 v90, v90, v91
	v_add_f32_e32 v89, v89, v90
	v_fmac_f32_e32 v89, 0x3fb8aa3b, v68
	v_cndmask_b32_e32 v68, v73, v89, vcc
	s_or_b32 s14, s6, 4
	s_ashr_i32 s15, s14, 31
	s_lshl_b64 s[14:15], s[14:15], 12
	s_add_u32 s16, s22, s14
	s_addc_u32 s17, s23, s15
	v_lshl_add_u64 v[150:151], s[16:17], 0, v[12:13]
	global_load_dwordx4 v[90:93], v[150:151], off
	global_load_dwordx4 v[94:97], v[150:151], off offset:16
	global_load_dwordx4 v[98:101], v[150:151], off offset:32
	global_load_dwordx4 v[102:105], v[150:151], off offset:48
	global_load_dwordx4 v[106:109], v[150:151], off offset:64
	global_load_dwordx4 v[110:113], v[150:151], off offset:80
	global_load_dwordx4 v[114:117], v[150:151], off offset:96
	global_load_dwordx4 v[118:121], v[150:151], off offset:112
	global_load_dwordx4 v[122:125], v[150:151], off offset:128
	global_load_dwordx4 v[126:129], v[150:151], off offset:144
	global_load_dwordx4 v[130:133], v[150:151], off offset:160
	global_load_dwordx4 v[134:137], v[150:151], off offset:176
	global_load_dwordx4 v[138:141], v[150:151], off offset:192
	global_load_dwordx4 v[142:145], v[150:151], off offset:208
	v_max_i32_e32 v89, 4, v4
	v_mov_b32_e32 v147, v3
	v_lshlrev_b32_e32 v146, 4, v89
	v_lshl_add_u64 v[146:147], v[10:11], 0, v[146:147]
	v_lshl_add_u64 v[146:147], v[146:147], 2, s[48:49]
	global_load_dword v89, v[146:147], off offset:-256
	s_nop 0
	global_load_dwordx4 v[146:149], v[150:151], off offset:240
	s_nop 0
	global_load_dwordx4 v[150:153], v[150:151], off offset:224
	v_cmp_lt_u32_e32 vcc, 3, v4
	s_waitcnt vmcnt(16)
	v_mul_f32_e32 v91, v91, v37
	v_mul_f32_e32 v93, v93, v38
	s_waitcnt vmcnt(15)
	v_mul_f32_e32 v95, v95, v39
	v_mul_f32_e32 v97, v97, v40
	v_fmac_f32_e32 v91, v90, v14
	v_fmac_f32_e32 v93, v92, v15
	s_waitcnt vmcnt(14)
	v_mul_f32_e32 v99, v99, v41
	v_mul_f32_e32 v101, v101, v42
	v_fmac_f32_e32 v95, v94, v16
	v_fmac_f32_e32 v97, v96, v17
	v_add_f32_e32 v90, v91, v93
	s_waitcnt vmcnt(13)
	v_mul_f32_e32 v103, v103, v43
	v_mul_f32_e32 v105, v105, v51
	v_fmac_f32_e32 v99, v98, v18
	v_fmac_f32_e32 v101, v100, v19
	v_add_f32_e32 v91, v95, v97
	v_add_f32_e32 v90, 0, v90
	s_waitcnt vmcnt(12)
	v_mul_f32_e32 v107, v107, v52
	v_mul_f32_e32 v109, v109, v59
	v_fmac_f32_e32 v103, v102, v20
	v_fmac_f32_e32 v105, v104, v21
	v_add_f32_e32 v92, v99, v101
	v_add_f32_e32 v90, v90, v91
	s_waitcnt vmcnt(11)
	v_mul_f32_e32 v111, v111, v60
	v_mul_f32_e32 v113, v113, v65
	v_fmac_f32_e32 v107, v106, v22
	v_fmac_f32_e32 v109, v108, v23
	v_add_f32_e32 v93, v103, v105
	v_add_f32_e32 v90, v90, v92
	s_waitcnt vmcnt(10)
	v_mul_f32_e32 v115, v115, v66
	v_mul_f32_e32 v117, v117, v67
	v_fmac_f32_e32 v111, v110, v24
	v_fmac_f32_e32 v113, v112, v25
	v_add_f32_e32 v94, v107, v109
	v_add_f32_e32 v90, v90, v93
	s_waitcnt vmcnt(9)
	v_mul_f32_e32 v119, v119, v69
	v_mul_f32_e32 v121, v121, v75
	v_fmac_f32_e32 v115, v114, v26
	v_fmac_f32_e32 v117, v116, v27
	v_add_f32_e32 v95, v111, v113
	v_add_f32_e32 v90, v90, v94
	s_waitcnt vmcnt(8)
	v_mul_f32_e32 v123, v123, v76
	v_mul_f32_e32 v125, v125, v77
	v_fmac_f32_e32 v119, v118, v28
	v_fmac_f32_e32 v121, v120, v29
	v_add_f32_e32 v96, v115, v117
	v_add_f32_e32 v90, v90, v95
	s_waitcnt vmcnt(7)
	v_mul_f32_e32 v127, v127, v78
	v_mul_f32_e32 v129, v129, v79
	v_fmac_f32_e32 v123, v122, v30
	v_fmac_f32_e32 v125, v124, v31
	v_add_f32_e32 v97, v119, v121
	v_add_f32_e32 v90, v90, v96
	s_waitcnt vmcnt(6)
	v_mul_f32_e32 v131, v131, v80
	v_mul_f32_e32 v133, v133, v81
	v_fmac_f32_e32 v127, v126, v32
	v_fmac_f32_e32 v129, v128, v33
	v_add_f32_e32 v98, v123, v125
	v_add_f32_e32 v90, v90, v97
	s_waitcnt vmcnt(5)
	v_mul_f32_e32 v135, v135, v82
	v_mul_f32_e32 v137, v137, v86
	v_fmac_f32_e32 v131, v130, v34
	v_fmac_f32_e32 v133, v132, v35
	v_add_f32_e32 v99, v127, v129
	v_add_f32_e32 v90, v90, v98
	s_waitcnt vmcnt(4)
	v_mul_f32_e32 v139, v139, v87
	v_fmac_f32_e32 v135, v134, v36
	v_fmac_f32_e32 v137, v136, v83
	v_add_f32_e32 v100, v131, v133
	v_add_f32_e32 v90, v90, v99
	v_mul_f32_e32 v91, v141, v88
	v_add_f32_e32 v101, v135, v137
	v_add_f32_e32 v90, v90, v100
	v_fmac_f32_e32 v139, v138, v84
	v_fmac_f32_e32 v91, v140, v85
	v_add_f32_e32 v90, v90, v101
	v_add_f32_e32 v91, v139, v91
	v_add_f32_e32 v90, v90, v91
	s_waitcnt vmcnt(3)
	v_mul_f32_e32 v91, v143, v61
	v_mul_f32_e32 v92, v145, v62
	v_fmac_f32_e32 v91, v142, v53
	v_fmac_f32_e32 v92, v144, v54
	v_add_f32_e32 v91, v91, v92
	v_add_f32_e32 v90, v90, v91
	s_waitcnt vmcnt(0)
	v_mul_f32_e32 v91, v151, v63
	v_mul_f32_e32 v92, v153, v64
	v_fmac_f32_e32 v91, v150, v55
	v_fmac_f32_e32 v92, v152, v56
	v_add_f32_e32 v91, v91, v92
	v_add_f32_e32 v90, v90, v91
	v_mul_f32_e32 v91, v147, v57
	v_mul_f32_e32 v92, v149, v58
	v_fmac_f32_e32 v91, v146, v49
	v_fmac_f32_e32 v92, v148, v50
	v_add_f32_e32 v91, v91, v92
	v_add_f32_e32 v90, v90, v91
	v_fmac_f32_e32 v90, 0x3fb8aa3b, v89
	v_cndmask_b32_e32 v89, v73, v90, vcc
	s_or_b32 s16, s6, 5
	s_ashr_i32 s17, s16, 31
	s_lshl_b64 s[16:17], s[16:17], 12
	s_add_u32 s18, s22, s16
	s_addc_u32 s19, s23, s17
	v_lshl_add_u64 v[150:151], s[18:19], 0, v[12:13]
	global_load_dwordx4 v[90:93], v[150:151], off
	global_load_dwordx4 v[94:97], v[150:151], off offset:16
	global_load_dwordx4 v[98:101], v[150:151], off offset:32
	global_load_dwordx4 v[102:105], v[150:151], off offset:48
	global_load_dwordx4 v[106:109], v[150:151], off offset:64
	global_load_dwordx4 v[110:113], v[150:151], off offset:80
	global_load_dwordx4 v[114:117], v[150:151], off offset:96
	global_load_dwordx4 v[118:121], v[150:151], off offset:112
	global_load_dwordx4 v[122:125], v[150:151], off offset:128
	global_load_dwordx4 v[126:129], v[150:151], off offset:144
	global_load_dwordx4 v[130:133], v[150:151], off offset:160
	global_load_dwordx4 v[134:137], v[150:151], off offset:176
	global_load_dwordx4 v[138:141], v[150:151], off offset:192
	global_load_dwordx4 v[142:145], v[150:151], off offset:208
	v_max_i32_e32 v146, 5, v4
	v_mov_b32_e32 v147, v3
	v_lshlrev_b32_e32 v146, 4, v146
	v_lshl_add_u64 v[146:147], v[10:11], 0, v[146:147]
	v_lshl_add_u64 v[146:147], v[146:147], 2, s[48:49]
	global_load_dword v154, v[146:147], off offset:-320
	s_nop 0
	global_load_dwordx4 v[146:149], v[150:151], off offset:240
	s_nop 0
	global_load_dwordx4 v[150:153], v[150:151], off offset:224
	v_cmp_lt_u32_e32 vcc, 4, v4
	s_waitcnt vmcnt(16)
	v_mul_f32_e32 v91, v91, v37
	v_mul_f32_e32 v93, v93, v38
	s_waitcnt vmcnt(15)
	v_mul_f32_e32 v95, v95, v39
	v_mul_f32_e32 v97, v97, v40
	v_fmac_f32_e32 v91, v90, v14
	v_fmac_f32_e32 v93, v92, v15
	s_waitcnt vmcnt(14)
	v_mul_f32_e32 v99, v99, v41
	v_mul_f32_e32 v101, v101, v42
	v_fmac_f32_e32 v95, v94, v16
	v_fmac_f32_e32 v97, v96, v17
	v_add_f32_e32 v90, v91, v93
	s_waitcnt vmcnt(13)
	v_mul_f32_e32 v103, v103, v43
	v_mul_f32_e32 v105, v105, v51
	v_fmac_f32_e32 v99, v98, v18
	v_fmac_f32_e32 v101, v100, v19
	v_add_f32_e32 v91, v95, v97
	v_add_f32_e32 v90, 0, v90
	s_waitcnt vmcnt(12)
	v_mul_f32_e32 v107, v107, v52
	v_mul_f32_e32 v109, v109, v59
	v_fmac_f32_e32 v103, v102, v20
	v_fmac_f32_e32 v105, v104, v21
	v_add_f32_e32 v92, v99, v101
	v_add_f32_e32 v90, v90, v91
	s_waitcnt vmcnt(11)
	v_mul_f32_e32 v111, v111, v60
	v_mul_f32_e32 v113, v113, v65
	v_fmac_f32_e32 v107, v106, v22
	v_fmac_f32_e32 v109, v108, v23
	v_add_f32_e32 v93, v103, v105
	v_add_f32_e32 v90, v90, v92
	s_waitcnt vmcnt(10)
	v_mul_f32_e32 v115, v115, v66
	v_mul_f32_e32 v117, v117, v67
	v_fmac_f32_e32 v111, v110, v24
	v_fmac_f32_e32 v113, v112, v25
	v_add_f32_e32 v94, v107, v109
	v_add_f32_e32 v90, v90, v93
	s_waitcnt vmcnt(9)
	v_mul_f32_e32 v119, v119, v69
	v_mul_f32_e32 v121, v121, v75
	v_fmac_f32_e32 v115, v114, v26
	v_fmac_f32_e32 v117, v116, v27
	v_add_f32_e32 v95, v111, v113
	v_add_f32_e32 v90, v90, v94
	s_waitcnt vmcnt(8)
	v_mul_f32_e32 v123, v123, v76
	v_mul_f32_e32 v125, v125, v77
	v_fmac_f32_e32 v119, v118, v28
	v_fmac_f32_e32 v121, v120, v29
	v_add_f32_e32 v96, v115, v117
	v_add_f32_e32 v90, v90, v95
	s_waitcnt vmcnt(7)
	v_mul_f32_e32 v127, v127, v78
	v_mul_f32_e32 v129, v129, v79
	v_fmac_f32_e32 v123, v122, v30
	v_fmac_f32_e32 v125, v124, v31
	v_add_f32_e32 v97, v119, v121
	v_add_f32_e32 v90, v90, v96
	s_waitcnt vmcnt(6)
	v_mul_f32_e32 v131, v131, v80
	v_mul_f32_e32 v133, v133, v81
	v_fmac_f32_e32 v127, v126, v32
	v_fmac_f32_e32 v129, v128, v33
	v_add_f32_e32 v98, v123, v125
	v_add_f32_e32 v90, v90, v97
	s_waitcnt vmcnt(5)
	v_mul_f32_e32 v135, v135, v82
	v_mul_f32_e32 v137, v137, v86
	v_fmac_f32_e32 v131, v130, v34
	v_fmac_f32_e32 v133, v132, v35
	v_add_f32_e32 v99, v127, v129
	v_add_f32_e32 v90, v90, v98
	s_waitcnt vmcnt(4)
	v_mul_f32_e32 v139, v139, v87
	v_fmac_f32_e32 v135, v134, v36
	v_fmac_f32_e32 v137, v136, v83
	v_add_f32_e32 v100, v131, v133
	v_add_f32_e32 v90, v90, v99
	v_mul_f32_e32 v91, v141, v88
	v_add_f32_e32 v101, v135, v137
	v_add_f32_e32 v90, v90, v100
	v_fmac_f32_e32 v139, v138, v84
	v_fmac_f32_e32 v91, v140, v85
	v_add_f32_e32 v90, v90, v101
	v_add_f32_e32 v91, v139, v91
	v_add_f32_e32 v90, v90, v91
	s_waitcnt vmcnt(3)
	v_mul_f32_e32 v91, v143, v61
	v_mul_f32_e32 v92, v145, v62
	v_fmac_f32_e32 v91, v142, v53
	v_fmac_f32_e32 v92, v144, v54
	v_add_f32_e32 v91, v91, v92
	v_add_f32_e32 v90, v90, v91
	s_waitcnt vmcnt(0)
	v_mul_f32_e32 v91, v151, v63
	v_mul_f32_e32 v92, v153, v64
	v_fmac_f32_e32 v91, v150, v55
	v_fmac_f32_e32 v92, v152, v56
	v_add_f32_e32 v91, v91, v92
	v_add_f32_e32 v90, v90, v91
	v_mul_f32_e32 v91, v147, v57
	v_mul_f32_e32 v92, v149, v58
	v_fmac_f32_e32 v91, v146, v49
	v_fmac_f32_e32 v92, v148, v50
	v_add_f32_e32 v91, v91, v92
	v_add_f32_e32 v90, v90, v91
	v_fmac_f32_e32 v90, 0x3fb8aa3b, v154
	v_cndmask_b32_e32 v90, v73, v90, vcc
	s_or_b32 s18, s6, 6
	s_ashr_i32 s19, s18, 31
	s_lshl_b64 s[18:19], s[18:19], 12
	s_add_u32 s38, s22, s18
	s_addc_u32 s39, s23, s19
	v_lshl_add_u64 v[152:153], s[38:39], 0, v[12:13]
	global_load_dwordx4 v[92:95], v[152:153], off
	global_load_dwordx4 v[96:99], v[152:153], off offset:16
	global_load_dwordx4 v[100:103], v[152:153], off offset:32
	global_load_dwordx4 v[104:107], v[152:153], off offset:48
	global_load_dwordx4 v[108:111], v[152:153], off offset:64
	global_load_dwordx4 v[112:115], v[152:153], off offset:80
	global_load_dwordx4 v[116:119], v[152:153], off offset:96
	global_load_dwordx4 v[120:123], v[152:153], off offset:112
	global_load_dwordx4 v[124:127], v[152:153], off offset:128
	global_load_dwordx4 v[128:131], v[152:153], off offset:144
	global_load_dwordx4 v[132:135], v[152:153], off offset:160
	global_load_dwordx4 v[136:139], v[152:153], off offset:176
	global_load_dwordx4 v[140:143], v[152:153], off offset:192
	global_load_dwordx4 v[144:147], v[152:153], off offset:208
	v_max_i32_e32 v91, 6, v4
	v_mov_b32_e32 v149, v3
	v_lshlrev_b32_e32 v148, 4, v91
	v_lshl_add_u64 v[148:149], v[10:11], 0, v[148:149]
	v_lshl_add_u64 v[148:149], v[148:149], 2, s[48:49]
	global_load_dword v91, v[148:149], off offset:-384
	s_nop 0
	global_load_dwordx4 v[148:151], v[152:153], off offset:240
	s_nop 0
	global_load_dwordx4 v[152:155], v[152:153], off offset:224
	v_cmp_lt_u32_e32 vcc, 5, v4
	s_waitcnt vmcnt(16)
	v_mul_f32_e32 v93, v93, v37
	v_mul_f32_e32 v95, v95, v38
	s_waitcnt vmcnt(15)
	v_mul_f32_e32 v97, v97, v39
	v_mul_f32_e32 v99, v99, v40
	v_fmac_f32_e32 v93, v92, v14
	v_fmac_f32_e32 v95, v94, v15
	s_waitcnt vmcnt(14)
	v_mul_f32_e32 v101, v101, v41
	v_mul_f32_e32 v103, v103, v42
	v_fmac_f32_e32 v97, v96, v16
	v_fmac_f32_e32 v99, v98, v17
	v_add_f32_e32 v92, v93, v95
	s_waitcnt vmcnt(13)
	v_mul_f32_e32 v105, v105, v43
	v_mul_f32_e32 v107, v107, v51
	v_fmac_f32_e32 v101, v100, v18
	v_fmac_f32_e32 v103, v102, v19
	v_add_f32_e32 v93, v97, v99
	v_add_f32_e32 v92, 0, v92
	s_waitcnt vmcnt(12)
	v_mul_f32_e32 v109, v109, v52
	v_mul_f32_e32 v111, v111, v59
	v_fmac_f32_e32 v105, v104, v20
	v_fmac_f32_e32 v107, v106, v21
	v_add_f32_e32 v94, v101, v103
	v_add_f32_e32 v92, v92, v93
	s_waitcnt vmcnt(11)
	v_mul_f32_e32 v113, v113, v60
	v_mul_f32_e32 v115, v115, v65
	v_fmac_f32_e32 v109, v108, v22
	v_fmac_f32_e32 v111, v110, v23
	v_add_f32_e32 v95, v105, v107
	v_add_f32_e32 v92, v92, v94
	s_waitcnt vmcnt(10)
	v_mul_f32_e32 v117, v117, v66
	v_mul_f32_e32 v119, v119, v67
	v_fmac_f32_e32 v113, v112, v24
	v_fmac_f32_e32 v115, v114, v25
	v_add_f32_e32 v96, v109, v111
	v_add_f32_e32 v92, v92, v95
	s_waitcnt vmcnt(9)
	v_mul_f32_e32 v121, v121, v69
	v_mul_f32_e32 v123, v123, v75
	v_fmac_f32_e32 v117, v116, v26
	v_fmac_f32_e32 v119, v118, v27
	v_add_f32_e32 v97, v113, v115
	v_add_f32_e32 v92, v92, v96
	s_waitcnt vmcnt(8)
	v_mul_f32_e32 v125, v125, v76
	v_mul_f32_e32 v127, v127, v77
	v_fmac_f32_e32 v121, v120, v28
	v_fmac_f32_e32 v123, v122, v29
	v_add_f32_e32 v98, v117, v119
	v_add_f32_e32 v92, v92, v97
	s_waitcnt vmcnt(7)
	v_mul_f32_e32 v129, v129, v78
	v_mul_f32_e32 v131, v131, v79
	v_fmac_f32_e32 v125, v124, v30
	v_fmac_f32_e32 v127, v126, v31
	v_add_f32_e32 v99, v121, v123
	v_add_f32_e32 v92, v92, v98
	s_waitcnt vmcnt(6)
	v_mul_f32_e32 v133, v133, v80
	v_mul_f32_e32 v135, v135, v81
	v_fmac_f32_e32 v129, v128, v32
	v_fmac_f32_e32 v131, v130, v33
	v_add_f32_e32 v100, v125, v127
	v_add_f32_e32 v92, v92, v99
	s_waitcnt vmcnt(5)
	v_mul_f32_e32 v137, v137, v82
	v_mul_f32_e32 v139, v139, v86
	v_fmac_f32_e32 v133, v132, v34
	v_fmac_f32_e32 v135, v134, v35
	v_add_f32_e32 v101, v129, v131
	v_add_f32_e32 v92, v92, v100
	s_waitcnt vmcnt(4)
	v_mul_f32_e32 v141, v141, v87
	v_fmac_f32_e32 v137, v136, v36
	v_fmac_f32_e32 v139, v138, v83
	v_add_f32_e32 v102, v133, v135
	v_add_f32_e32 v92, v92, v101
	v_mul_f32_e32 v93, v143, v88
	v_add_f32_e32 v103, v137, v139
	v_add_f32_e32 v92, v92, v102
	v_fmac_f32_e32 v141, v140, v84
	v_fmac_f32_e32 v93, v142, v85
	v_add_f32_e32 v92, v92, v103
	v_add_f32_e32 v93, v141, v93
	v_add_f32_e32 v92, v92, v93
	s_waitcnt vmcnt(3)
	v_mul_f32_e32 v93, v145, v61
	v_mul_f32_e32 v94, v147, v62
	v_fmac_f32_e32 v93, v144, v53
	v_fmac_f32_e32 v94, v146, v54
	v_add_f32_e32 v93, v93, v94
	v_add_f32_e32 v92, v92, v93
	s_waitcnt vmcnt(0)
	v_mul_f32_e32 v93, v153, v63
	v_mul_f32_e32 v94, v155, v64
	v_fmac_f32_e32 v93, v152, v55
	v_fmac_f32_e32 v94, v154, v56
	v_add_f32_e32 v93, v93, v94
	v_add_f32_e32 v92, v92, v93
	v_mul_f32_e32 v93, v149, v57
	v_mul_f32_e32 v94, v151, v58
	v_fmac_f32_e32 v93, v148, v49
	v_fmac_f32_e32 v94, v150, v50
	v_add_f32_e32 v93, v93, v94
	v_add_f32_e32 v92, v92, v93
	v_fmac_f32_e32 v92, 0x3fb8aa3b, v91
	v_cndmask_b32_e32 v91, v73, v92, vcc
	s_or_b32 s6, s6, 7
	s_ashr_i32 s7, s6, 31
	s_lshl_b64 s[6:7], s[6:7], 12
	s_add_u32 s38, s22, s6
	s_addc_u32 s39, s23, s7
	v_lshl_add_u64 v[148:149], s[38:39], 0, v[12:13]
	global_load_dwordx4 v[92:95], v[148:149], off
	global_load_dwordx4 v[96:99], v[148:149], off offset:16
	global_load_dwordx4 v[100:103], v[148:149], off offset:32
	global_load_dwordx4 v[104:107], v[148:149], off offset:48
	global_load_dwordx4 v[108:111], v[148:149], off offset:64
	global_load_dwordx4 v[112:115], v[148:149], off offset:80
	global_load_dwordx4 v[116:119], v[148:149], off offset:96
	global_load_dwordx4 v[120:123], v[148:149], off offset:112
	global_load_dwordx4 v[124:127], v[148:149], off offset:128
	global_load_dwordx4 v[128:131], v[148:149], off offset:144
	global_load_dwordx4 v[132:135], v[148:149], off offset:160
	global_load_dwordx4 v[136:139], v[148:149], off offset:176
	global_load_dwordx4 v[140:143], v[148:149], off offset:192
	global_load_dwordx4 v[144:147], v[148:149], off offset:208
	v_lshl_add_u64 v[10:11], v[10:11], 2, s[48:49]
	global_load_dword v152, v[10:11], off
	s_nop 0
	global_load_dwordx4 v[10:13], v[148:149], off offset:240
	s_nop 0
	global_load_dwordx4 v[148:151], v[148:149], off offset:224
	v_cmp_eq_u32_e32 vcc, 7, v4
	s_waitcnt vmcnt(16)
	v_mul_f32_e32 v37, v93, v37
	v_mul_f32_e32 v38, v95, v38
	s_waitcnt vmcnt(15)
	v_mul_f32_e32 v39, v97, v39
	v_mul_f32_e32 v40, v99, v40
	v_fmac_f32_e32 v37, v92, v14
	v_fmac_f32_e32 v38, v94, v15
	s_waitcnt vmcnt(14)
	v_mul_f32_e32 v41, v101, v41
	v_mul_f32_e32 v42, v103, v42
	v_fmac_f32_e32 v39, v96, v16
	v_fmac_f32_e32 v40, v98, v17
	v_add_f32_e32 v14, v37, v38
	s_waitcnt vmcnt(13)
	v_mul_f32_e32 v43, v105, v43
	v_mul_f32_e32 v51, v107, v51
	v_fmac_f32_e32 v41, v100, v18
	v_fmac_f32_e32 v42, v102, v19
	v_add_f32_e32 v15, v39, v40
	v_add_f32_e32 v14, 0, v14
	s_waitcnt vmcnt(12)
	v_mul_f32_e32 v52, v109, v52
	v_mul_f32_e32 v59, v111, v59
	v_fmac_f32_e32 v43, v104, v20
	v_fmac_f32_e32 v51, v106, v21
	v_add_f32_e32 v16, v41, v42
	v_add_f32_e32 v14, v14, v15
	s_waitcnt vmcnt(11)
	v_mul_f32_e32 v60, v113, v60
	v_mul_f32_e32 v65, v115, v65
	v_fmac_f32_e32 v52, v108, v22
	v_fmac_f32_e32 v59, v110, v23
	v_add_f32_e32 v17, v43, v51
	v_add_f32_e32 v14, v14, v16
	s_waitcnt vmcnt(10)
	v_mul_f32_e32 v66, v117, v66
	v_mul_f32_e32 v67, v119, v67
	v_fmac_f32_e32 v60, v112, v24
	v_fmac_f32_e32 v65, v114, v25
	v_add_f32_e32 v18, v52, v59
	v_add_f32_e32 v14, v14, v17
	s_waitcnt vmcnt(9)
	v_mul_f32_e32 v69, v121, v69
	v_mul_f32_e32 v75, v123, v75
	v_fmac_f32_e32 v66, v116, v26
	v_fmac_f32_e32 v67, v118, v27
	v_add_f32_e32 v19, v60, v65
	v_add_f32_e32 v14, v14, v18
	s_waitcnt vmcnt(8)
	v_mul_f32_e32 v76, v125, v76
	v_mul_f32_e32 v77, v127, v77
	v_fmac_f32_e32 v69, v120, v28
	v_fmac_f32_e32 v75, v122, v29
	v_add_f32_e32 v20, v66, v67
	v_add_f32_e32 v14, v14, v19
	s_waitcnt vmcnt(7)
	v_mul_f32_e32 v78, v129, v78
	v_mul_f32_e32 v79, v131, v79
	v_fmac_f32_e32 v76, v124, v30
	v_fmac_f32_e32 v77, v126, v31
	v_add_f32_e32 v21, v69, v75
	v_add_f32_e32 v14, v14, v20
	s_waitcnt vmcnt(6)
	v_mul_f32_e32 v80, v133, v80
	v_mul_f32_e32 v81, v135, v81
	v_fmac_f32_e32 v78, v128, v32
	v_fmac_f32_e32 v79, v130, v33
	v_add_f32_e32 v22, v76, v77
	v_add_f32_e32 v14, v14, v21
	s_waitcnt vmcnt(5)
	v_mul_f32_e32 v82, v137, v82
	v_mul_f32_e32 v86, v139, v86
	v_fmac_f32_e32 v80, v132, v34
	v_fmac_f32_e32 v81, v134, v35
	v_add_f32_e32 v23, v78, v79
	v_add_f32_e32 v14, v14, v22
	s_waitcnt vmcnt(4)
	v_mul_f32_e32 v87, v141, v87
	v_mul_f32_e32 v88, v143, v88
	v_fmac_f32_e32 v82, v136, v36
	v_fmac_f32_e32 v86, v138, v83
	v_add_f32_e32 v24, v80, v81
	v_add_f32_e32 v14, v14, v23
	v_fmac_f32_e32 v87, v140, v84
	v_fmac_f32_e32 v88, v142, v85
	v_add_f32_e32 v25, v82, v86
	v_add_f32_e32 v14, v14, v24
	s_waitcnt vmcnt(3)
	v_mul_f32_e32 v15, v145, v61
	v_mul_f32_e32 v16, v147, v62
	v_add_f32_e32 v26, v87, v88
	v_add_f32_e32 v14, v14, v25
	v_fmac_f32_e32 v15, v144, v53
	v_fmac_f32_e32 v16, v146, v54
	v_add_f32_e32 v14, v14, v26
	v_add_f32_e32 v15, v15, v16
	v_add_f32_e32 v14, v14, v15
	s_waitcnt vmcnt(0)
	v_mul_f32_e32 v15, v149, v63
	v_mul_f32_e32 v16, v151, v64
	v_mul_f32_e32 v11, v11, v57
	v_fmac_f32_e32 v15, v148, v55
	v_fmac_f32_e32 v16, v150, v56
	v_fmac_f32_e32 v11, v10, v49
	v_mul_f32_e32 v10, v13, v58
	v_add_f32_e32 v15, v15, v16
	v_fmac_f32_e32 v10, v12, v50
	v_add_f32_e32 v14, v14, v15
	v_add_f32_e32 v10, v11, v10
	v_add_f32_e32 v10, v14, v10
	v_fmac_f32_e32 v10, 0x3fb8aa3b, v152
	v_cndmask_b32_e32 v49, v73, v10, vcc
	v_readlane_b32 s98, v254, 27
	s_nop 3
	s_cmp_lg_u32 s98, 0
	s_cbranch_scc1 .Lcmb_wait_done
	s_mov_b32 s99, 0
	v_mov_b32_e32 v51, 0
.Lcmb_spin:
	global_load_dword v50, v51, s[100:101] sc1
	s_waitcnt vmcnt(0)
	v_readfirstlane_b32 s98, v50
	s_cmp_gt_u32 s98, 15
	s_cbranch_scc1 .Lcmb_acq
	s_sleep 2
	s_add_u32 s99, s99, 1
	s_cmp_lt_u32 s99, 0x400000
	s_cbranch_scc1 .Lcmb_spin

.Lcmb_wait_done:
	s_barrier
	global_load_dwordx4 v[50:53], v[6:7], off
	global_load_dwordx4 v[54:57], v[6:7], off offset:16
	global_load_dwordx4 v[58:61], v[6:7], off offset:32
	global_load_dwordx4 v[62:65], v[6:7], off offset:48
	s_mov_b32 s33, 1
	v_mov_b32_e32 v4, v5
	v_mov_b32_e32 v39, v5
	v_mov_b32_e32 v38, v5
	v_mov_b32_e32 v11, v5
	v_mov_b32_e32 v10, v5
	v_mov_b32_e32 v13, v5
	v_mov_b32_e32 v12, v5
	v_mov_b32_e32 v15, v5
	v_mov_b32_e32 v14, v5
	v_mov_b32_e32 v17, v5
	v_mov_b32_e32 v16, v5
	v_mov_b32_e32 v19, v5
	v_mov_b32_e32 v18, v5
	v_mov_b32_e32 v21, v5
	v_mov_b32_e32 v20, v5
	v_mov_b32_e32 v23, v5
	v_mov_b32_e32 v22, v5
	v_mov_b32_e32 v25, v5
	v_mov_b32_e32 v24, v5
	v_mov_b32_e32 v27, v5
	v_mov_b32_e32 v26, v5
	v_mov_b32_e32 v29, v5
	v_mov_b32_e32 v28, v5
	v_mov_b32_e32 v31, v5
	v_mov_b32_e32 v30, v5
	v_mov_b32_e32 v33, v5
	v_mov_b32_e32 v32, v5
	v_mov_b32_e32 v35, v5
	v_mov_b32_e32 v34, v5
	v_mov_b32_e32 v37, v5
	v_mov_b32_e32 v36, v5
	v_mov_b32_e32 v40, v5
	v_mov_b32_e32 v43, v5
	v_mov_b32_e32 v42, v5
	s_cmp_lt_i32 s33, 1
	s_waitcnt vmcnt(3)
	v_max_f32_e32 v41, v53, v53
	v_max_f32_e32 v52, v52, v52
	s_waitcnt vmcnt(2)
	v_max_f32_e32 v53, v57, v57
	v_max_f32_e32 v56, v56, v56
	s_waitcnt vmcnt(1)
	v_max_f32_e32 v57, v61, v61
	v_max_f32_e32 v60, v60, v60
	s_waitcnt vmcnt(0)
	v_max_f32_e32 v61, v65, v65
	v_max_f32_e32 v64, v64, v64
	v_max_f32_e32 v41, v52, v41
	v_max_f32_e32 v52, v56, v53
	v_max_f32_e32 v53, v60, v57
	v_max_f32_e32 v56, v64, v61
	v_max3_f32 v41, v50, v51, v41
	v_max3_f32 v50, v54, v55, v52
	v_max3_f32 v51, v58, v59, v53
	v_max3_f32 v52, v62, v63, v56
	v_max3_f32 v41, v41, s37, v50
	v_max3_f32 v41, v41, v51, v52
	v_max3_f32 v41, v41, v45, v47
	v_max3_f32 v41, v41, v48, v68
	v_max3_f32 v41, v41, v89, v90
	v_max3_f32 v50, v41, v91, v49
	v_mov_b32_e32 v51, v5
	s_cbranch_scc1 .LBB0_828
	v_readlane_b32 s24, v254, 63
	v_lshlrev_b64 v[4:5], 4, v[8:9]
	v_readlane_b32 s25, v255, 0
	v_mov_b32_e32 v10, s20
	v_lshlrev_b32_e32 v12, 9, v46
	v_lshl_add_u64 v[8:9], v[4:5], 2, s[24:25]
	v_mov_b32_e32 v4, s21
	v_bfe_i32 v4, v4, 0, 8
	v_mov_b32_e32 v13, v3
	v_ashrrev_i32_e32 v5, 31, v4
	v_bfe_i32 v10, v10, 0, 8
	v_lshl_add_u64 v[12:13], s[26:27], 0, v[12:13]
	v_lshlrev_b32_e32 v14, 4, v74
	v_mov_b32_e32 v15, v3
	v_ashrrev_i32_e32 v11, 31, v10
	v_lshl_add_u64 v[12:13], v[12:13], 0, v[14:15]
	v_lshlrev_b64 v[4:5], 20, v[4:5]
	v_lshlrev_b64 v[10:11], 13, v[10:11]
	v_lshl_add_u64 v[4:5], v[12:13], 0, v[4:5]
	v_mov_b32_e32 v51, 0
	v_lshl_add_u64 v[40:41], v[4:5], 0, v[10:11]
	s_lshl_b32 s20, s28, 1
	v_mov_b32_e32 v38, 0
	v_mov_b32_e32 v39, v51
	v_mov_b32_e32 v4, 0
	v_mov_b32_e32 v5, v51
	v_mov_b32_e32 v36, 0
	v_mov_b32_e32 v37, v51
	v_mov_b32_e32 v34, 0
	v_mov_b32_e32 v35, v51
	v_mov_b32_e32 v32, 0
	v_mov_b32_e32 v33, v51
	v_mov_b32_e32 v30, 0
	v_mov_b32_e32 v31, v51
	v_mov_b32_e32 v28, 0
	v_mov_b32_e32 v29, v51
	v_mov_b32_e32 v26, 0
	v_mov_b32_e32 v27, v51
	v_mov_b32_e32 v24, 0
	v_mov_b32_e32 v25, v51
	v_mov_b32_e32 v22, 0
	v_mov_b32_e32 v23, v51
	v_mov_b32_e32 v20, 0
	v_mov_b32_e32 v21, v51
	v_mov_b32_e32 v18, 0
	v_mov_b32_e32 v19, v51
	v_mov_b32_e32 v16, 0
	v_mov_b32_e32 v17, v51
	v_mov_b32_e32 v14, 0
	v_mov_b32_e32 v15, v51
	v_mov_b32_e32 v12, 0
	v_mov_b32_e32 v13, v51
	v_mov_b32_e32 v10, 0
	v_mov_b32_e32 v11, v51
